# attention: stage-end barrier and LDS tile writes moved ahead of the last four P.V MFMAs (all LDS reads of the stage are done by then)
# speedup vs baseline: 1.0094x; 1.0038x over previous
; #define SBAR() __builtin_amdgcn_sched_barrier(0)
; #define SLOAD(i, k0) do { const char* vt_ = (const char*)Vh + (size_t)(k0) * 256; const char* kt_ = (const char*)Kh + (size_t)(k0) * 128; \
;     sr_[i].vs0 = *reinterpret_cast<const bf16x8*>(vt_ + voff0); sr_[i].vs1 = *reinterpret_cast<const bf16x8*>(vt_ + 32 * 256 + voff0); \
;     sr_[i].ks0 = *reinterpret_cast<const bf16x8*>(kt_ + koff0); } while (0)
; #define SBAR() __builtin_amdgcn_sched_barrier(0)
; __device__ __forceinline__ void attn_unit(const bf16* __restrict__ Qb, const bf16* __restrict__ Kh, const bf16* __restrict__ Vh, bf16* __restrict__ Ob, int seq, char* lds) {
;     ...
;         SBAR(); qkt(pB0, pB1, K_lds + SHM_K, qr, r32, hi); pv_ks<0>(o, vb0, pa0); SBAR();
;         softHalf(pA1, l_reg, pa2, pa3); SBAR();
;         SLOAD(SO, (j + 1) * KVBLK); SBAR();
;         pv_ks<1>(o, vb0, pa1); pv_ks<2>(o, vb0, pa2); pv_ks<3>(o, vb0, pa3); SBAR();
;         softHalf(pB0, l_reg, pa0, pa1); SBAR();
.LBB0_531:
	ds_read_b128 v[82:85], v157 offset:40960
	ds_read_b128 v[86:89], v157 offset:45056
	ds_read_b128 v[164:167], v159 offset:40960
	ds_read_b128 v[168:171], v159 offset:45056
	ds_read_b128 v[188:191], v162 offset:40960
	ds_read_b128 v[230:233], v162 offset:45056
	ds_read_b128 v[234:237], v163 offset:40960
	ds_read_b128 v[242:245], v163 offset:45056
	v_exp_f32_e32 v66, v66
	v_exp_f32_e32 v67, v67
	v_exp_f32_e32 v68, v68
	v_exp_f32_e32 v69, v69
	s_waitcnt lgkmcnt(7)
	v_mfma_f32_32x32x16_bf16 v[98:113], v[82:85], v[126:129], 0
	v_exp_f32_e32 v70, v70
	v_add_f32_e32 v179, 0, v66
	s_waitcnt lgkmcnt(6)
	v_mfma_f32_32x32x16_bf16 v[82:97], v[86:89], v[126:129], 0
	v_exp_f32_e32 v71, v71
	v_add_f32_e32 v179, v67, v179
	v_exp_f32_e32 v72, v72
	v_add_f32_e32 v179, v68, v179
	s_waitcnt lgkmcnt(5)
	v_mfma_f32_32x32x16_bf16 v[98:113], v[164:167], v[122:125], v[98:113]
	v_exp_f32_e32 v73, v73
	v_add_f32_e32 v179, v69, v179
	v_exp_f32_e32 v74, v74
	s_waitcnt lgkmcnt(4)
	v_mfma_f32_32x32x16_bf16 v[82:97], v[168:171], v[122:125], v[82:97]
	ds_read_b64_tr_b16 v[172:173], v156 offset:0
	ds_read_b64_tr_b16 v[174:175], v156 offset:0x800
	ds_read_b64_tr_b16 v[164:165], v156 offset:0x200
	ds_read_b64_tr_b16 v[166:167], v156 offset:0xa00
	ds_read_b64_tr_b16 v[180:181], v156 offset:0x400
	ds_read_b64_tr_b16 v[182:183], v156 offset:0xc00
	ds_read_b64_tr_b16 v[184:185], v156 offset:0x600
	ds_read_b64_tr_b16 v[186:187], v156 offset:0xe00
	v_add_f32_e32 v179, v70, v179
	v_exp_f32_e32 v75, v75
	v_add_f32_e32 v179, v71, v179
	s_waitcnt lgkmcnt(11)
	v_mfma_f32_32x32x16_bf16 v[98:113], v[188:191], v[118:121], v[98:113]
	v_exp_f32_e32 v76, v76
	v_add_f32_e32 v179, v72, v179
	v_exp_f32_e32 v77, v77
	s_waitcnt lgkmcnt(10)
	v_mfma_f32_32x32x16_bf16 v[82:97], v[230:233], v[118:121], v[82:97]
	v_add_f32_e32 v179, v73, v179
	v_exp_f32_e32 v78, v78
	v_add_f32_e32 v179, v74, v179
	s_waitcnt lgkmcnt(9)
	v_mfma_f32_32x32x16_bf16 v[98:113], v[234:237], v[114:117], v[98:113]
	v_exp_f32_e32 v79, v79
	v_add_f32_e32 v179, v75, v179
	v_exp_f32_e32 v80, v80
	s_waitcnt lgkmcnt(8)
	v_mfma_f32_32x32x16_bf16 v[82:97], v[242:245], v[114:117], v[82:97]
	v_add_f32_e32 v179, v76, v179
	v_exp_f32_e32 v81, v81
	v_add_f32_e32 v179, v77, v179
	v_add_f32_e32 v179, v78, v179
	s_waitcnt lgkmcnt(6)
	v_mfma_f32_32x32x16_bf16 v[2:17], v[134:137], v[172:175], v[2:17]
	ds_read_b64_tr_b16 v[188:189], v156 offset:0x1000
	ds_read_b64_tr_b16 v[190:191], v156 offset:0x1800
	ds_read_b64_tr_b16 v[230:231], v156 offset:0x1200
	ds_read_b64_tr_b16 v[232:233], v156 offset:0x1a00
	ds_read_b64_tr_b16 v[234:235], v156 offset:0x1400
	ds_read_b64_tr_b16 v[236:237], v156 offset:0x1c00
	ds_read_b64_tr_b16 v[242:243], v156 offset:0x1600
	ds_read_b64_tr_b16 v[244:245], v156 offset:0x1e00
	v_add_f32_e32 v179, v79, v179
	v_add_f32_e32 v179, v80, v179
	v_add_f32_e32 v179, v81, v179
	v_cvt_pk_bf16_f32 v66, v66, v67
	s_waitcnt lgkmcnt(12)
	v_mfma_f32_32x32x16_bf16 v[18:33], v[134:137], v[164:167], v[18:33]
	v_cvt_pk_bf16_f32 v67, v68, v69
	v_cvt_pk_bf16_f32 v68, v70, v71
	v_cvt_pk_bf16_f32 v69, v72, v73
	v_cvt_pk_bf16_f32 v70, v74, v75
	s_waitcnt lgkmcnt(10)
	v_mfma_f32_32x32x16_bf16 v[34:49], v[134:137], v[180:183], v[34:49]
	v_cvt_pk_bf16_f32 v71, v76, v77
	v_cvt_pk_bf16_f32 v72, v78, v79
	v_cvt_pk_bf16_f32 v73, v80, v81
	v_add_f32_e32 v221, v139, v179
	s_waitcnt lgkmcnt(8)
	v_mfma_f32_32x32x16_bf16 v[50:65], v[134:137], v[184:187], v[50:65]
	v_lshl_add_u64 v[136:137], s[30:31], 0, v[148:149]
	v_add_co_u32_e32 v74, vcc, s40, v136
	v_lshl_add_u64 v[150:151], s[30:31], 0, v[146:147]
	s_nop 0
	v_addc_co_u32_e32 v75, vcc, 0, v137, vcc
	v_add_co_u32_e32 v78, vcc, s41, v136
	s_nop 1
	v_addc_co_u32_e32 v79, vcc, 0, v137, vcc
	v_add_co_u32_e32 v164, vcc, s42, v150
	s_waitcnt lgkmcnt(6)
	v_mfma_f32_32x32x16_bf16 v[2:17], v[130:133], v[188:191], v[2:17]
	ds_read_b64_tr_b16 v[168:169], v156 offset:0x2000
	ds_read_b64_tr_b16 v[170:171], v156 offset:0x2800
	ds_read_b64_tr_b16 v[172:173], v156 offset:0x2200
	ds_read_b64_tr_b16 v[174:175], v156 offset:0x2a00
	ds_read_b64_tr_b16 v[180:181], v156 offset:0x2400
	ds_read_b64_tr_b16 v[182:183], v156 offset:0x2c00
	ds_read_b64_tr_b16 v[184:185], v156 offset:0x2600
	ds_read_b64_tr_b16 v[186:187], v156 offset:0x2e00
	global_load_dwordx4 v[74:77], v[74:75], off
	s_nop 0
	global_load_dwordx4 v[78:81], v[78:79], off
	v_addc_co_u32_e32 v165, vcc, 0, v151, vcc
	global_load_dwordx4 v[164:167], v[164:165], off
	s_waitcnt lgkmcnt(12)
	v_mfma_f32_32x32x16_bf16 v[18:33], v[130:133], v[230:233], v[18:33]
	v_exp_f32_e32 v220, v98
	v_exp_f32_e32 v177, v99
	v_exp_f32_e32 v193, v100
	s_waitcnt lgkmcnt(10)
	v_mfma_f32_32x32x16_bf16 v[34:49], v[130:133], v[234:237], v[34:49]
	v_exp_f32_e32 v195, v101
	v_exp_f32_e32 v197, v102
	v_exp_f32_e32 v199, v103
	s_waitcnt lgkmcnt(8)
	v_mfma_f32_32x32x16_bf16 v[50:65], v[130:133], v[242:245], v[50:65]
	v_exp_f32_e32 v201, v104
	v_exp_f32_e32 v203, v105
	v_cvt_pk_bf16_f32 v222, v220, v177
	v_cvt_pk_bf16_f32 v223, v193, v195
	s_waitcnt lgkmcnt(6)
	v_mfma_f32_32x32x16_bf16 v[2:17], v[66:69], v[168:171], v[2:17]
	ds_read_b64_tr_b16 v[188:189], v156 offset:0x3000
	ds_read_b64_tr_b16 v[190:191], v156 offset:0x3800
	ds_read_b64_tr_b16 v[230:231], v156 offset:0x3200
	ds_read_b64_tr_b16 v[232:233], v156 offset:0x3a00
	ds_read_b64_tr_b16 v[234:235], v156 offset:0x3400
	ds_read_b64_tr_b16 v[236:237], v156 offset:0x3c00
	ds_read_b64_tr_b16 v[242:243], v156 offset:0x3600
	ds_read_b64_tr_b16 v[244:245], v156 offset:0x3e00
	v_cvt_pk_bf16_f32 v224, v197, v199
	v_cvt_pk_bf16_f32 v225, v201, v203
	v_exp_f32_e32 v205, v106
	s_waitcnt lgkmcnt(12)
	v_mfma_f32_32x32x16_bf16 v[18:33], v[66:69], v[172:175], v[18:33]
	v_exp_f32_e32 v207, v107
	v_exp_f32_e32 v209, v108
	v_exp_f32_e32 v211, v109
	s_waitcnt lgkmcnt(10)
	v_mfma_f32_32x32x16_bf16 v[34:49], v[66:69], v[180:183], v[34:49]
	v_exp_f32_e32 v213, v110
	v_exp_f32_e32 v215, v111
	v_exp_f32_e32 v217, v112
	s_waitcnt lgkmcnt(8)
	v_mfma_f32_32x32x16_bf16 v[50:65], v[66:69], v[184:187], v[50:65]
	s_waitcnt lgkmcnt(0)
	s_barrier
; #define SBAR() __builtin_amdgcn_sched_barrier(0)
; #define SLOAD(i, k0) do { const char* vt_ = (const char*)Vh + (size_t)(k0) * 256; const char* kt_ = (const char*)Kh + (size_t)(k0) * 128; \
;     sr_[i].vs0 = *reinterpret_cast<const bf16x8*>(vt_ + voff0); sr_[i].vs1 = *reinterpret_cast<const bf16x8*>(vt_ + 32 * 256 + voff0); \
;     sr_[i].ks0 = *reinterpret_cast<const bf16x8*>(kt_ + koff0); } while (0)
; #define SWRITE(b, i) do { *(bf16x8*)(V_lds + (b) * SHM_V + vst0) = sr_[i].vs0; *(bf16x8*)(V_lds + (b) * SHM_V + vst1) = sr_[i].vs1; \
;     *(bf16x8*)(K_lds + (b) * SHM_K + kst) = sr_[i].ks0; } while (0)
; #define SWAIT() asm volatile("s_waitcnt vmcnt(0)" ::: "memory")
; #define SBAR() __builtin_amdgcn_sched_barrier(0)
; __device__ __forceinline__ void attn_unit(const bf16* __restrict__ Qb, const bf16* __restrict__ Kh, const bf16* __restrict__ Vh, bf16* __restrict__ Ob, int seq, char* lds) {
;     ...
;         __syncthreads(); SWAIT(); SWRITE(0, SE);
;         __syncthreads();
;         SBAR(); qkt(pA0, pA1, K_lds, qr, r32, hi); pv_ks<0>(o, vb0 + SHM_V, pa0); SBAR();
;         softHalf(pB1, l_reg, pa2, pa3); SBAR();
;         SLOAD(SE, (j + 2) * KVBLK); SBAR();
;         pv_ks<1>(o, vb0 + SHM_V, pa1); pv_ks<2>(o, vb0 + SHM_V, pa2); pv_ks<3>(o, vb0 + SHM_V, pa3); SBAR();
;         softHalf(pA0, l_reg, pa0, pa1); SBAR();
	s_waitcnt vmcnt(0)
	s_waitcnt vmcnt(2)
	ds_write_b128 v160, v[74:77]
	s_waitcnt vmcnt(1)
	ds_write_b128 v161, v[78:81]
	s_waitcnt vmcnt(0)
	ds_write_b128 v158, v[164:167] offset:32768
	v_exp_f32_e32 v219, v113
	v_add_f32_e32 v139, 0, v220
	v_add_f32_e32 v238, v177, v139
	v_add_f32_e32 v238, v193, v238
	v_add_f32_e32 v238, v195, v238
	v_mfma_f32_32x32x16_bf16 v[2:17], v[70:73], v[188:191], v[2:17]
	v_add_f32_e32 v238, v197, v238
	v_add_f32_e32 v238, v199, v238
	v_add_f32_e32 v238, v201, v238
	v_add_f32_e32 v238, v203, v238
	v_add_f32_e32 v238, v205, v238
	v_add_f32_e32 v238, v207, v238
	v_mfma_f32_32x32x16_bf16 v[18:33], v[70:73], v[230:233], v[18:33]
	v_add_f32_e32 v238, v209, v238
	v_add_f32_e32 v238, v211, v238
	v_add_f32_e32 v238, v213, v238
	v_add_f32_e32 v238, v215, v238
	v_add_f32_e32 v238, v217, v238
	v_add_f32_e32 v238, v219, v238
	v_mfma_f32_32x32x16_bf16 v[34:49], v[70:73], v[234:237], v[34:49]
	v_add_f32_e32 v238, v221, v238
	v_cvt_pk_bf16_f32 v226, v205, v207
	v_cvt_pk_bf16_f32 v227, v209, v211
	v_cvt_pk_bf16_f32 v228, v213, v215
	v_cvt_pk_bf16_f32 v229, v217, v219
	v_mfma_f32_32x32x16_bf16 v[50:65], v[70:73], v[242:245], v[50:65]
	s_waitcnt lgkmcnt(0)
	s_barrier
	ds_read_b128 v[66:69], v157 offset:32768
	ds_read_b128 v[70:73], v157 offset:36864
	ds_read_b128 v[164:167], v159 offset:32768
	ds_read_b128 v[172:175], v159 offset:36864
	ds_read_b128 v[230:233], v162 offset:32768
	ds_read_b128 v[234:237], v162 offset:36864
	ds_read_b128 v[168:171], v163 offset:32768
	ds_read_b128 v[242:245], v163 offset:36864
	v_exp_f32_e32 v176, v82
	v_exp_f32_e32 v192, v83
	v_exp_f32_e32 v194, v84
	v_exp_f32_e32 v196, v85
	s_waitcnt lgkmcnt(7)
	v_mfma_f32_32x32x16_bf16 v[98:113], v[66:69], v[126:129], 0
	v_exp_f32_e32 v198, v86
	v_add_f32_e32 v82, v176, v138
	s_waitcnt lgkmcnt(6)
	v_mfma_f32_32x32x16_bf16 v[66:81], v[70:73], v[126:129], 0
	v_exp_f32_e32 v200, v87
	v_add_f32_e32 v82, v192, v82
	v_exp_f32_e32 v202, v88
	v_add_f32_e32 v82, v194, v82
	s_waitcnt lgkmcnt(5)
	v_mfma_f32_32x32x16_bf16 v[98:113], v[164:167], v[122:125], v[98:113]
	v_exp_f32_e32 v204, v89
	v_add_f32_e32 v82, v196, v82
	v_exp_f32_e32 v206, v90
	s_waitcnt lgkmcnt(4)
	v_mfma_f32_32x32x16_bf16 v[66:81], v[172:175], v[122:125], v[66:81]
	ds_read_b64_tr_b16 v[180:181], v141 offset:0
	ds_read_b64_tr_b16 v[182:183], v141 offset:0x800
	ds_read_b64_tr_b16 v[164:165], v141 offset:0x200
	ds_read_b64_tr_b16 v[166:167], v141 offset:0xa00
	ds_read_b64_tr_b16 v[184:185], v141 offset:0x400
	ds_read_b64_tr_b16 v[186:187], v141 offset:0xc00
	ds_read_b64_tr_b16 v[188:189], v141 offset:0x600
	ds_read_b64_tr_b16 v[190:191], v141 offset:0xe00
	v_add_f32_e32 v82, v198, v82
	v_exp_f32_e32 v208, v91
	v_add_f32_e32 v82, v200, v82
	s_waitcnt lgkmcnt(11)
	v_mfma_f32_32x32x16_bf16 v[98:113], v[230:233], v[118:121], v[98:113]
	v_exp_f32_e32 v210, v92
	v_add_f32_e32 v82, v202, v82
	v_exp_f32_e32 v212, v93
	s_waitcnt lgkmcnt(10)
	v_mfma_f32_32x32x16_bf16 v[66:81], v[234:237], v[118:121], v[66:81]
	v_add_f32_e32 v82, v204, v82
	v_exp_f32_e32 v214, v94
	v_add_f32_e32 v82, v206, v82
	s_waitcnt lgkmcnt(9)
	v_mfma_f32_32x32x16_bf16 v[98:113], v[168:171], v[114:117], v[98:113]
	v_exp_f32_e32 v216, v95
	v_add_f32_e32 v82, v208, v82
	v_exp_f32_e32 v218, v96
	s_waitcnt lgkmcnt(8)
	v_mfma_f32_32x32x16_bf16 v[66:81], v[242:245], v[114:117], v[66:81]
	v_add_f32_e32 v82, v210, v82
	v_exp_f32_e32 v220, v97
	v_add_f32_e32 v82, v212, v82
	v_add_f32_e32 v82, v214, v82
	s_waitcnt lgkmcnt(6)
	v_mfma_f32_32x32x16_bf16 v[2:17], v[222:225], v[180:183], v[2:17]
	ds_read_b64_tr_b16 v[230:231], v141 offset:0x1000
	ds_read_b64_tr_b16 v[232:233], v141 offset:0x1800
	ds_read_b64_tr_b16 v[234:235], v141 offset:0x1200
	ds_read_b64_tr_b16 v[236:237], v141 offset:0x1a00
	ds_read_b64_tr_b16 v[168:169], v141 offset:0x1400
	ds_read_b64_tr_b16 v[170:171], v141 offset:0x1c00
	ds_read_b64_tr_b16 v[172:173], v141 offset:0x1600
	ds_read_b64_tr_b16 v[174:175], v141 offset:0x1e00
	v_add_f32_e32 v82, v216, v82
	v_add_f32_e32 v82, v218, v82
	v_add_f32_e32 v82, v220, v82
	v_add_f32_e32 v139, v82, v238
	s_waitcnt lgkmcnt(12)
	v_mfma_f32_32x32x16_bf16 v[18:33], v[222:225], v[164:167], v[18:33]
	v_cvt_pk_bf16_f32 v82, v176, v192
	v_cvt_pk_bf16_f32 v83, v194, v196
	v_cvt_pk_bf16_f32 v84, v198, v200
	v_cvt_pk_bf16_f32 v85, v202, v204
	s_waitcnt lgkmcnt(10)
	v_mfma_f32_32x32x16_bf16 v[34:49], v[222:225], v[184:187], v[34:49]
	v_cvt_pk_bf16_f32 v86, v206, v208
	v_cvt_pk_bf16_f32 v87, v210, v212
	v_cvt_pk_bf16_f32 v88, v214, v216
	v_cvt_pk_bf16_f32 v89, v218, v220
	s_waitcnt lgkmcnt(8)
	v_mfma_f32_32x32x16_bf16 v[50:65], v[222:225], v[188:191], v[50:65]
	v_add_co_u32_e32 v90, vcc, s43, v136
	s_nop 1
	v_addc_co_u32_e32 v91, vcc, 0, v137, vcc
	v_add_co_u32_e32 v94, vcc, s46, v136
	s_nop 1
	v_addc_co_u32_e32 v95, vcc, 0, v137, vcc
	v_add_co_u32_e32 v130, vcc, s47, v150
	global_load_dwordx4 v[90:93], v[90:91], off
	s_nop 0
	s_waitcnt lgkmcnt(6)
	v_mfma_f32_32x32x16_bf16 v[2:17], v[226:229], v[230:233], v[2:17]
	ds_read_b64_tr_b16 v[180:181], v141 offset:0x2000
	ds_read_b64_tr_b16 v[182:183], v141 offset:0x2800
	ds_read_b64_tr_b16 v[184:185], v141 offset:0x2200
	ds_read_b64_tr_b16 v[186:187], v141 offset:0x2a00
	ds_read_b64_tr_b16 v[188:189], v141 offset:0x2400
	ds_read_b64_tr_b16 v[190:191], v141 offset:0x2c00
	ds_read_b64_tr_b16 v[222:223], v141 offset:0x2600
	ds_read_b64_tr_b16 v[224:225], v141 offset:0x2e00
	global_load_dwordx4 v[94:97], v[94:95], off
	v_addc_co_u32_e32 v131, vcc, 0, v151, vcc
	global_load_dwordx4 v[164:167], v[130:131], off
	v_exp_f32_e32 v239, v98
	s_waitcnt lgkmcnt(12)
; #define SBAR() __builtin_amdgcn_sched_barrier(0)
; #define SWRITE(b, i) do { *(bf16x8*)(V_lds + (b) * SHM_V + vst0) = sr_[i].vs0; *(bf16x8*)(V_lds + (b) * SHM_V + vst1) = sr_[i].vs1; \
;     *(bf16x8*)(K_lds + (b) * SHM_K + kst) = sr_[i].ks0; } while (0)
; #define SWAIT() asm volatile("s_waitcnt vmcnt(0)" ::: "memory")
; #define SBAR() __builtin_amdgcn_sched_barrier(0)
; __device__ __forceinline__ void attn_unit(const bf16* __restrict__ Qb, const bf16* __restrict__ Kh, const bf16* __restrict__ Vh, bf16* __restrict__ Ob, int seq, char* lds) {
;     ...
;         pv_ks<1>(o, vb0 + SHM_V, pa1); pv_ks<2>(o, vb0 + SHM_V, pa2); pv_ks<3>(o, vb0 + SHM_V, pa3); SBAR();
;         softHalf(pA0, l_reg, pa0, pa1); SBAR();
;         __syncthreads(); SWAIT(); SWRITE(1, SO);
;         __syncthreads();
;     }
;     SBAR(); qkt(pB0, pB1, K_lds + SHM_K, qr, r32, hi); pv_ks<0>(o, vb0, pa0); SBAR();
;     softHalf(pA1, l_reg, pa2, pa3); SBAR();
;     pv_ks<1>(o, vb0, pa1); pv_ks<2>(o, vb0, pa2); pv_ks<3>(o, vb0, pa3); SBAR();
	v_mfma_f32_32x32x16_bf16 v[18:33], v[226:229], v[234:237], v[18:33]
	v_exp_f32_e32 v241, v99
	v_exp_f32_e32 v242, v100
	v_exp_f32_e32 v243, v101
	s_waitcnt lgkmcnt(10)
	v_mfma_f32_32x32x16_bf16 v[34:49], v[226:229], v[168:171], v[34:49]
	v_exp_f32_e32 v244, v102
	v_exp_f32_e32 v98, v106
	v_add_f32_e32 v106, 0, v239
	s_waitcnt lgkmcnt(8)
	v_mfma_f32_32x32x16_bf16 v[50:65], v[226:229], v[172:175], v[50:65]
	v_exp_f32_e32 v245, v103
	v_add_f32_e32 v106, v241, v106
	v_exp_f32_e32 v246, v104
	v_add_f32_e32 v106, v242, v106
	s_waitcnt lgkmcnt(6)
	v_mfma_f32_32x32x16_bf16 v[2:17], v[82:85], v[180:183], v[2:17]
	ds_read_b64_tr_b16 v[230:231], v141 offset:0x3000
	ds_read_b64_tr_b16 v[232:233], v141 offset:0x3800
	ds_read_b64_tr_b16 v[234:235], v141 offset:0x3200
	ds_read_b64_tr_b16 v[236:237], v141 offset:0x3a00
	ds_read_b64_tr_b16 v[168:169], v141 offset:0x3400
	ds_read_b64_tr_b16 v[170:171], v141 offset:0x3c00
	ds_read_b64_tr_b16 v[172:173], v141 offset:0x3600
	ds_read_b64_tr_b16 v[174:175], v141 offset:0x3e00
	v_exp_f32_e32 v247, v105
	v_add_f32_e32 v106, v243, v106
	v_add_f32_e32 v106, v244, v106
	v_exp_f32_e32 v99, v107
	s_waitcnt lgkmcnt(12)
	v_mfma_f32_32x32x16_bf16 v[18:33], v[82:85], v[184:187], v[18:33]
	v_add_f32_e32 v106, v245, v106
	v_exp_f32_e32 v100, v108
	v_add_f32_e32 v106, v246, v106
	v_exp_f32_e32 v101, v109
	s_waitcnt lgkmcnt(10)
	v_mfma_f32_32x32x16_bf16 v[34:49], v[82:85], v[188:191], v[34:49]
	v_add_f32_e32 v106, v247, v106
	v_exp_f32_e32 v102, v110
	v_add_f32_e32 v106, v98, v106
	v_exp_f32_e32 v103, v111
	s_waitcnt lgkmcnt(8)
	v_mfma_f32_32x32x16_bf16 v[50:65], v[82:85], v[222:225], v[50:65]
	s_waitcnt lgkmcnt(0)
	s_barrier
	s_waitcnt vmcnt(0)
	s_add_i32 s10, s10, 2
	v_lshl_add_u64 v[146:147], v[146:147], 0, s[0:1]
	s_cmp_gt_u32 s10, 32
	v_lshl_add_u64 v[148:149], v[148:149], 0, s[4:5]
	s_waitcnt vmcnt(2)
	ds_write_b128 v160, v[90:93] offset:16384
	s_waitcnt vmcnt(1)
	ds_write_b128 v161, v[94:97] offset:16384
	s_waitcnt vmcnt(0)
	ds_write_b128 v158, v[164:167] offset:40960
	v_add_f32_e32 v106, v99, v106
	v_exp_f32_e32 v104, v112
	v_add_f32_e32 v106, v100, v106
	v_mfma_f32_32x32x16_bf16 v[2:17], v[86:89], v[230:233], v[2:17]
	v_exp_f32_e32 v105, v113
	v_add_f32_e32 v106, v101, v106
	v_add_f32_e32 v106, v102, v106
	v_add_f32_e32 v106, v103, v106
	v_add_f32_e32 v106, v104, v106
	v_add_f32_e32 v106, v105, v106
	v_mfma_f32_32x32x16_bf16 v[18:33], v[86:89], v[234:237], v[18:33]
	v_cvt_pk_bf16_f32 v134, v239, v241
	v_cvt_pk_bf16_f32 v135, v242, v243
	v_cvt_pk_bf16_f32 v136, v244, v245
	v_cvt_pk_bf16_f32 v137, v246, v247
	v_mfma_f32_32x32x16_bf16 v[34:49], v[86:89], v[168:171], v[34:49]
	v_cvt_pk_bf16_f32 v130, v98, v99
	v_cvt_pk_bf16_f32 v131, v100, v101
	v_cvt_pk_bf16_f32 v132, v102, v103
	v_cvt_pk_bf16_f32 v133, v104, v105
	v_add_f32_e32 v139, v139, v106
	v_mfma_f32_32x32x16_bf16 v[50:65], v[86:89], v[172:175], v[50:65]
	s_waitcnt lgkmcnt(0)
	s_barrier
	s_cbranch_scc0 .LBB0_531
	v_and_b32_e32 v82, 0x3fffffc0, v143
	v_lshl_add_u32 v143, v82, 2, 0
	ds_read_b128 v[82:85], v157 offset:40960
	ds_read_b128 v[86:89], v157 offset:45056
	s_waitcnt lgkmcnt(1)
	v_mfma_f32_32x32x16_bf16 v[98:113], v[82:85], v[126:129], 0
	s_waitcnt lgkmcnt(0)
	v_mfma_f32_32x32x16_bf16 v[82:97], v[86:89], v[126:129], 0
	ds_read_b128 v[126:129], v159 offset:40960
	ds_read_b128 v[146:149], v159 offset:45056
	s_waitcnt lgkmcnt(1)
	v_mfma_f32_32x32x16_bf16 v[98:113], v[126:129], v[122:125], v[98:113]
	s_waitcnt lgkmcnt(0)
	v_mfma_f32_32x32x16_bf16 v[82:97], v[146:149], v[122:125], v[82:97]
	ds_read_b128 v[122:125], v162 offset:40960
	ds_read_b128 v[126:129], v162 offset:45056
	s_waitcnt lgkmcnt(1)
	v_mfma_f32_32x32x16_bf16 v[98:113], v[122:125], v[118:121], v[98:113]
	s_waitcnt lgkmcnt(0)
	v_mfma_f32_32x32x16_bf16 v[82:97], v[126:129], v[118:121], v[82:97]
	ds_read_b128 v[118:121], v163 offset:40960
	ds_read_b128 v[122:125], v163 offset:45056
	ds_read_b64_tr_b16 v[126:127], v156 offset:0
	ds_read_b64_tr_b16 v[128:129], v156 offset:0x800
	s_waitcnt lgkmcnt(1)
	v_mfma_f32_32x32x16_bf16 v[98:113], v[118:121], v[114:117], v[98:113]
	ds_read_b64_tr_b16 v[118:119], v156 offset:0x200
	ds_read_b64_tr_b16 v[120:121], v156 offset:0xa00
	ds_read_b64_tr_b16 v[146:147], v156 offset:0x400
	ds_read_b64_tr_b16 v[148:149], v156 offset:0xc00
	ds_read_b64_tr_b16 v[158:159], v156 offset:0x600
	ds_read_b64_tr_b16 v[160:161], v156 offset:0xe00
	s_waitcnt lgkmcnt(0)
	s_waitcnt lgkmcnt(0)
	v_mfma_f32_32x32x16_bf16 v[82:97], v[122:125], v[114:117], v[82:97]
	v_mfma_f32_32x32x16_bf16 v[2:17], v[134:137], v[126:129], v[2:17]
	v_mfma_f32_32x32x16_bf16 v[18:33], v[134:137], v[118:121], v[18:33]
	v_mfma_f32_32x32x16_bf16 v[34:49], v[134:137], v[146:149], v[34:49]
	v_mfma_f32_32x32x16_bf16 v[50:65], v[134:137], v[158:161], v[50:65]
	v_exp_f32_e32 v66, v66
	v_exp_f32_e32 v67, v67
	v_exp_f32_e32 v68, v68
	v_exp_f32_e32 v69, v69
	v_exp_f32_e32 v70, v70
	v_add_f32_e32 v114, 0, v66
	v_exp_f32_e32 v71, v71
	v_add_f32_e32 v114, v67, v114
	v_exp_f32_e32 v72, v72
	v_add_f32_e32 v114, v68, v114
	v_exp_f32_e32 v73, v73
	v_add_f32_e32 v114, v69, v114
	v_exp_f32_e32 v74, v74
	v_add_f32_e32 v114, v70, v114
	v_exp_f32_e32 v75, v75
	v_add_f32_e32 v114, v71, v114
	v_exp_f32_e32 v76, v76
	v_add_f32_e32 v114, v72, v114
	v_exp_f32_e32 v77, v77
	v_add_f32_e32 v114, v73, v114
	v_exp_f32_e32 v78, v78
	v_add_f32_e32 v114, v74, v114
	v_exp_f32_e32 v79, v79
	v_add_f32_e32 v114, v75, v114
	v_exp_f32_e32 v80, v80
	v_add_f32_e32 v114, v76, v114
	v_exp_f32_e32 v81, v81
	v_add_f32_e32 v114, v77, v114
	v_add_f32_e32 v114, v78, v114
	v_add_f32_e32 v114, v79, v114
	v_add_f32_e32 v114, v80, v114
	v_cvt_pk_bf16_f32 v66, v66, v67
	v_cvt_pk_bf16_f32 v67, v68, v69
	v_cvt_pk_bf16_f32 v68, v70, v71
	v_cvt_pk_bf16_f32 v69, v72, v73
	v_add_f32_e32 v114, v81, v114
	v_cvt_pk_bf16_f32 v70, v74, v75
	v_cvt_pk_bf16_f32 v71, v76, v77
	v_cvt_pk_bf16_f32 v72, v78, v79
	v_cvt_pk_bf16_f32 v73, v80, v81
	v_add_f32_e32 v126, v139, v114
	ds_read_b64_tr_b16 v[74:75], v156 offset:0x1000
	ds_read_b64_tr_b16 v[76:77], v156 offset:0x1800
	ds_read_b64_tr_b16 v[78:79], v156 offset:0x1200
	ds_read_b64_tr_b16 v[80:81], v156 offset:0x1a00
	ds_read_b64_tr_b16 v[114:115], v156 offset:0x1400
	ds_read_b64_tr_b16 v[116:117], v156 offset:0x1c00
	ds_read_b64_tr_b16 v[118:119], v156 offset:0x1600
	ds_read_b64_tr_b16 v[120:121], v156 offset:0x1e00
	s_waitcnt lgkmcnt(0)
; #define SBAR() __builtin_amdgcn_sched_barrier(0)
; #define SBAR() __builtin_amdgcn_sched_barrier(0)
; __device__ __forceinline__ void attn_unit(const bf16* __restrict__ Qb, const bf16* __restrict__ Kh, const bf16* __restrict__ Vh, bf16* __restrict__ Ob, int seq, char* lds) {
;     ...
;     pv_ks<1>(o, vb0, pa1); pv_ks<2>(o, vb0, pa2); pv_ks<3>(o, vb0, pa3); SBAR();
;     softHalf(pB0, l_reg, pa0, pa1); SBAR();
;     pv_ks<0>(o, vb0 + SHM_V, pa0); SBAR();
;     softHalf(pB1, l_reg, pa2, pa3); SBAR();
;     pv_ks<1>(o, vb0 + SHM_V, pa1); pv_ks<2>(o, vb0 + SHM_V, pa2); pv_ks<3>(o, vb0 + SHM_V, pa3);
;     { auto rr = __builtin_amdgcn_permlane32_swap(__float_as_uint(l_reg), __float_as_uint(l_reg), false, false); l_reg = __uint_as_float(rr[0]) + __uint_as_float(rr[1]); }
;     if (hi == 0) wsf[r32] = l_reg; asm volatile("s_waitcnt lgkmcnt(0)" ::: "memory");
	s_nop 0
	v_mfma_f32_32x32x16_bf16 v[2:17], v[130:133], v[74:77], v[2:17]
	ds_read_b64_tr_b16 v[74:75], v156 offset:0x2000
	ds_read_b64_tr_b16 v[76:77], v156 offset:0x2800
	v_mfma_f32_32x32x16_bf16 v[18:33], v[130:133], v[78:81], v[18:33]
	ds_read_b64_tr_b16 v[78:79], v156 offset:0x2200
	ds_read_b64_tr_b16 v[80:81], v156 offset:0x2a00
	v_mfma_f32_32x32x16_bf16 v[34:49], v[130:133], v[114:117], v[34:49]
	ds_read_b64_tr_b16 v[114:115], v156 offset:0x2400
	ds_read_b64_tr_b16 v[116:117], v156 offset:0x2c00
	ds_read_b64_tr_b16 v[122:123], v156 offset:0x2600
	ds_read_b64_tr_b16 v[124:125], v156 offset:0x2e00
	s_waitcnt lgkmcnt(0)
	v_mfma_f32_32x32x16_bf16 v[50:65], v[130:133], v[118:121], v[50:65]
	v_mfma_f32_32x32x16_bf16 v[2:17], v[66:69], v[74:77], v[2:17]
	ds_read_b64_tr_b16 v[74:75], v156 offset:0x3000
	ds_read_b64_tr_b16 v[76:77], v156 offset:0x3800
	v_mfma_f32_32x32x16_bf16 v[18:33], v[66:69], v[78:81], v[18:33]
	ds_read_b64_tr_b16 v[78:79], v156 offset:0x3200
	ds_read_b64_tr_b16 v[80:81], v156 offset:0x3a00
	v_mfma_f32_32x32x16_bf16 v[34:49], v[66:69], v[114:117], v[34:49]
	ds_read_b64_tr_b16 v[114:115], v156 offset:0x3400
	ds_read_b64_tr_b16 v[116:117], v156 offset:0x3c00
	ds_read_b64_tr_b16 v[118:119], v156 offset:0x3600
	ds_read_b64_tr_b16 v[120:121], v156 offset:0x3e00
	s_waitcnt lgkmcnt(0)
	v_mfma_f32_32x32x16_bf16 v[50:65], v[66:69], v[122:125], v[50:65]
	v_mfma_f32_32x32x16_bf16 v[2:17], v[70:73], v[74:77], v[2:17]
	v_mfma_f32_32x32x16_bf16 v[18:33], v[70:73], v[78:81], v[18:33]
	v_mfma_f32_32x32x16_bf16 v[34:49], v[70:73], v[114:117], v[34:49]
	v_mfma_f32_32x32x16_bf16 v[50:65], v[70:73], v[118:121], v[50:65]
	v_exp_f32_e32 v66, v98
	v_exp_f32_e32 v67, v99
	v_exp_f32_e32 v68, v100
	v_exp_f32_e32 v69, v101
	v_exp_f32_e32 v70, v102
	v_add_f32_e32 v98, 0, v66
	v_exp_f32_e32 v71, v103
	v_add_f32_e32 v98, v67, v98
	v_exp_f32_e32 v72, v104
	v_add_f32_e32 v98, v68, v98
	v_exp_f32_e32 v73, v105
	v_add_f32_e32 v98, v69, v98
	v_exp_f32_e32 v74, v106
	v_add_f32_e32 v98, v70, v98
	v_exp_f32_e32 v75, v107
	v_add_f32_e32 v98, v71, v98
	v_exp_f32_e32 v76, v108
	v_add_f32_e32 v98, v72, v98
	v_exp_f32_e32 v77, v109
	v_add_f32_e32 v98, v73, v98
	v_exp_f32_e32 v78, v110
	v_add_f32_e32 v98, v74, v98
	v_exp_f32_e32 v79, v111
	v_add_f32_e32 v98, v75, v98
	v_exp_f32_e32 v80, v112
	v_add_f32_e32 v98, v76, v98
	v_exp_f32_e32 v81, v113
	v_add_f32_e32 v98, v77, v98
	v_add_f32_e32 v98, v78, v98
	v_add_f32_e32 v98, v79, v98
	v_add_f32_e32 v98, v80, v98
	v_cvt_pk_bf16_f32 v66, v66, v67
	v_cvt_pk_bf16_f32 v67, v68, v69
	v_cvt_pk_bf16_f32 v68, v70, v71
	v_cvt_pk_bf16_f32 v69, v72, v73
	v_add_f32_e32 v98, v81, v98
	v_cvt_pk_bf16_f32 v70, v74, v75
	v_cvt_pk_bf16_f32 v71, v76, v77
	v_cvt_pk_bf16_f32 v72, v78, v79
	v_cvt_pk_bf16_f32 v73, v80, v81
	v_add_f32_e32 v106, v126, v98
	ds_read_b64_tr_b16 v[74:75], v141 offset:0
	ds_read_b64_tr_b16 v[76:77], v141 offset:0x800
	ds_read_b64_tr_b16 v[78:79], v141 offset:0x200
	ds_read_b64_tr_b16 v[80:81], v141 offset:0xa00
	ds_read_b64_tr_b16 v[98:99], v141 offset:0x400
	ds_read_b64_tr_b16 v[100:101], v141 offset:0xc00
	ds_read_b64_tr_b16 v[102:103], v141 offset:0x600
	ds_read_b64_tr_b16 v[104:105], v141 offset:0xe00
	s_waitcnt lgkmcnt(0)
	s_nop 0
	v_mfma_f32_32x32x16_bf16 v[2:17], v[66:69], v[74:77], v[2:17]
	v_mfma_f32_32x32x16_bf16 v[18:33], v[66:69], v[78:81], v[18:33]
	v_mfma_f32_32x32x16_bf16 v[34:49], v[66:69], v[98:101], v[34:49]
	v_mfma_f32_32x32x16_bf16 v[50:65], v[66:69], v[102:105], v[50:65]
	v_exp_f32_e32 v67, v82
	v_exp_f32_e32 v68, v83
	v_exp_f32_e32 v69, v84
	v_exp_f32_e32 v75, v85
	v_exp_f32_e32 v76, v86
	v_add_f32_e32 v66, 0, v67
	v_exp_f32_e32 v77, v87
	v_add_f32_e32 v66, v68, v66
	v_exp_f32_e32 v78, v88
	v_add_f32_e32 v66, v69, v66
	v_exp_f32_e32 v79, v89
	v_add_f32_e32 v66, v75, v66
	v_exp_f32_e32 v80, v90
	v_add_f32_e32 v66, v76, v66
	v_exp_f32_e32 v81, v91
	v_add_f32_e32 v66, v77, v66
	v_exp_f32_e32 v82, v92
	v_add_f32_e32 v66, v78, v66
	v_exp_f32_e32 v83, v93
	v_add_f32_e32 v66, v79, v66
	v_exp_f32_e32 v84, v94
	v_add_f32_e32 v66, v80, v66
	v_exp_f32_e32 v85, v95
	v_add_f32_e32 v66, v81, v66
	v_exp_f32_e32 v86, v96
	v_add_f32_e32 v66, v82, v66
	v_exp_f32_e32 v87, v97
	v_add_f32_e32 v66, v83, v66
	v_add_f32_e32 v66, v84, v66
	v_add_f32_e32 v66, v85, v66
	v_add_f32_e32 v66, v86, v66
	v_add_f32_e32 v66, v87, v66
	v_add_f32_e32 v66, v66, v106
	v_cvt_pk_bf16_f32 v74, v67, v68
	v_cvt_pk_bf16_f32 v75, v69, v75
	v_cvt_pk_bf16_f32 v76, v76, v77
	v_cvt_pk_bf16_f32 v77, v78, v79
	v_cvt_pk_bf16_f32 v78, v80, v81
	v_cvt_pk_bf16_f32 v79, v82, v83
	v_cvt_pk_bf16_f32 v80, v84, v85
	v_cvt_pk_bf16_f32 v81, v86, v87
	s_nop 0
	ds_read_b64_tr_b16 v[82:83], v141 offset:0x1000
	ds_read_b64_tr_b16 v[84:85], v141 offset:0x1800
	ds_read_b64_tr_b16 v[86:87], v141 offset:0x1200
	ds_read_b64_tr_b16 v[88:89], v141 offset:0x1a00
	ds_read_b64_tr_b16 v[90:91], v141 offset:0x1400
	ds_read_b64_tr_b16 v[92:93], v141 offset:0x1c00
	ds_read_b64_tr_b16 v[94:95], v141 offset:0x1600
	ds_read_b64_tr_b16 v[96:97], v141 offset:0x1e00
	s_waitcnt lgkmcnt(0)
	s_nop 0
	v_mfma_f32_32x32x16_bf16 v[2:17], v[70:73], v[82:85], v[2:17]
	ds_read_b64_tr_b16 v[82:83], v141 offset:0x2000
	ds_read_b64_tr_b16 v[84:85], v141 offset:0x2800
	v_mfma_f32_32x32x16_bf16 v[18:33], v[70:73], v[86:89], v[18:33]
	ds_read_b64_tr_b16 v[86:87], v141 offset:0x2200
	ds_read_b64_tr_b16 v[88:89], v141 offset:0x2a00
	v_mfma_f32_32x32x16_bf16 v[34:49], v[70:73], v[90:93], v[34:49]
	ds_read_b64_tr_b16 v[90:91], v141 offset:0x2400
	ds_read_b64_tr_b16 v[92:93], v141 offset:0x2c00
	ds_read_b64_tr_b16 v[98:99], v141 offset:0x2600
	ds_read_b64_tr_b16 v[100:101], v141 offset:0x2e00
	s_waitcnt lgkmcnt(0)
	v_mfma_f32_32x32x16_bf16 v[50:65], v[70:73], v[94:97], v[50:65]
	ds_read_b64_tr_b16 v[68:69], v141 offset:0x3000
	ds_read_b64_tr_b16 v[70:71], v141 offset:0x3800
	v_mfma_f32_32x32x16_bf16 v[2:17], v[74:77], v[82:85], v[2:17]
	ds_read_b64_tr_b16 v[82:83], v141 offset:0x3200
	ds_read_b64_tr_b16 v[84:85], v141 offset:0x3a00
	v_mfma_f32_32x32x16_bf16 v[18:33], v[74:77], v[86:89], v[18:33]
	ds_read_b64_tr_b16 v[86:87], v141 offset:0x3400
	ds_read_b64_tr_b16 v[88:89], v141 offset:0x3c00
	v_mfma_f32_32x32x16_bf16 v[34:49], v[74:77], v[90:93], v[34:49]
	ds_read_b64_tr_b16 v[90:91], v141 offset:0x3600
	ds_read_b64_tr_b16 v[92:93], v141 offset:0x3e00
	s_waitcnt lgkmcnt(0)
	v_mfma_f32_32x32x16_bf16 v[50:65], v[74:77], v[98:101], v[50:65]
	v_mfma_f32_32x32x16_bf16 v[2:17], v[78:81], v[68:71], v[2:17]
	v_mov_b32_e32 v67, v66
	s_nop 1
	v_permlane32_swap_b32_e32 v66, v67
	v_cmp_gt_u32_e32 vcc, 32, v145
	v_mfma_f32_32x32x16_bf16 v[18:33], v[78:81], v[82:85], v[18:33]
	v_mfma_f32_32x32x16_bf16 v[34:49], v[78:81], v[86:89], v[34:49]
	v_mfma_f32_32x32x16_bf16 v[50:65], v[78:81], v[90:93], v[50:65]
	s_and_saveexec_b64 s[10:11], vcc
	s_cbranch_execz .LBB0_529
	v_add_f32_e32 v66, v66, v67
	v_lshl_add_u32 v67, v153, 2, v143
	ds_write_b32 v67, v66 offset:49152
	s_branch .LBB0_529
